# P0 row sum of squares: the 6-step lane butterfly uses DPP (quad_perm, row_half_mirror, row_mirror) and v_permlane16/32_swap instead of 6 ds_bpermute + LDS waits
# baseline (speedup 1.0000x reference)
.LBB0_93:
	v_add_co_u32_e32 v16, vcc, 0xffffd000, v68
	s_nop 1
	v_addc_co_u32_e32 v17, vcc, -1, v69, vcc
	global_load_dwordx4 v[56:59], v[16:17], off offset:-3072 nt
	global_load_dwordx4 v[40:43], v[16:17], off offset:-2048 nt
	global_load_dwordx4 v[36:39], v[16:17], off offset:-1024 nt
	global_load_dwordx4 v[32:35], v[16:17], off nt
	global_load_dwordx4 v[12:15], v[68:69], off offset:-3072 nt
	global_load_dwordx4 v[8:11], v[68:69], off offset:-2048 nt
	global_load_dwordx4 v[4:7], v[68:69], off offset:-1024 nt
	global_load_dwordx4 v[0:3], v[68:69], off nt
	v_add_co_u32_e32 v16, vcc, 0xffffe000, v68
	s_waitcnt vmcnt(7)
	v_mul_f32_e32 v65, v57, v57
	v_addc_co_u32_e32 v17, vcc, -1, v69, vcc
	v_add_co_u32_e32 v72, vcc, 0xfffff000, v68
	global_load_dwordx4 v[60:63], v[16:17], off offset:-3072 nt
	global_load_dwordx4 v[52:55], v[16:17], off offset:-2048 nt
	global_load_dwordx4 v[48:51], v[16:17], off offset:-1024 nt
	global_load_dwordx4 v[44:47], v[16:17], off nt
	v_addc_co_u32_e32 v73, vcc, -1, v69, vcc
	global_load_dwordx4 v[28:31], v[72:73], off offset:-3072 nt
	global_load_dwordx4 v[24:27], v[72:73], off offset:-2048 nt
	s_waitcnt lgkmcnt(0)
	global_load_dwordx4 v[20:23], v[72:73], off offset:-1024 nt
	global_load_dwordx4 v[16:19], v[68:69], off offset:-4096 nt
	v_mul_f32_e32 v72, v59, v59
	s_waitcnt vmcnt(14)
	v_mul_f32_e32 v73, v41, v41
	v_mul_f32_e32 v74, v43, v43
	s_waitcnt vmcnt(13)
	v_mul_f32_e32 v75, v37, v37
	v_mul_f32_e32 v82, v39, v39
	v_fmac_f32_e32 v65, v56, v56
	v_fmac_f32_e32 v72, v58, v58
	v_fmac_f32_e32 v73, v40, v40
	v_fmac_f32_e32 v74, v42, v42
	s_waitcnt vmcnt(12)
	v_mul_f32_e32 v83, v33, v33
	v_mul_f32_e32 v84, v35, v35
	v_fmac_f32_e32 v75, v36, v36
	v_fmac_f32_e32 v82, v38, v38
	v_add_f32_e32 v65, v65, v72
	v_add_f32_e32 v72, v73, v74
	v_fmac_f32_e32 v83, v32, v32
	v_fmac_f32_e32 v84, v34, v34
	v_add_f32_e32 v73, v75, v82
	v_add_f32_e32 v65, v65, v72
	v_add_f32_e32 v74, v83, v84
	v_add_f32_e32 v65, v65, v73
	v_add_f32_e32 v65, v65, v74
	s_nop 1
	s_waitcnt lgkmcnt(0)
	v_add_f32_dpp v65, v65, v65 quad_perm:[1,0,3,2] row_mask:0xf bank_mask:0xf
	s_nop 1
	s_waitcnt lgkmcnt(0)
	v_add_f32_dpp v65, v65, v65 quad_perm:[2,3,0,1] row_mask:0xf bank_mask:0xf
	s_nop 1
	s_waitcnt lgkmcnt(0)
	v_add_f32_dpp v65, v65, v65 row_half_mirror row_mask:0xf bank_mask:0xf
	s_nop 1
	s_waitcnt lgkmcnt(0)
	v_add_f32_dpp v65, v65, v65 row_mirror row_mask:0xf bank_mask:0xf
	v_mov_b32_e32 v72, v65
	s_nop 1
	v_permlane16_swap_b32_e32 v72, v65
	s_waitcnt lgkmcnt(0)
	v_add_f32_e32 v65, v72, v65
	v_mov_b32_e32 v74, v65
	s_nop 1
	v_permlane32_swap_b32_e32 v74, v65
	v_lshl_add_u64 v[72:73], s[84:85], 0, v[70:71]
	s_and_saveexec_b64 s[20:21], s[2:3]
	s_cbranch_execz .LBB0_95
	s_waitcnt lgkmcnt(0)
	v_add_f32_e32 v65, v74, v65
	global_store_dword v[72:73], v65, off
.LBB0_95:
	s_or_b64 exec, exec, s[20:21]
	s_waitcnt vmcnt(7)
	v_mul_f32_e32 v65, v61, v61
	s_waitcnt lgkmcnt(0)
	v_mul_f32_e32 v74, v63, v63
	v_fmac_f32_e32 v65, v60, v60
	v_fmac_f32_e32 v74, v62, v62
	v_add_f32_e32 v65, v65, v74
	s_waitcnt vmcnt(6)
	v_mul_f32_e32 v74, v53, v53
	v_mul_f32_e32 v75, v55, v55
	v_fmac_f32_e32 v74, v52, v52
	v_fmac_f32_e32 v75, v54, v54
	v_add_f32_e32 v74, v74, v75
	v_add_f32_e32 v65, v65, v74
	s_waitcnt vmcnt(5)
	v_mul_f32_e32 v74, v49, v49
	v_mul_f32_e32 v75, v51, v51
	v_fmac_f32_e32 v74, v48, v48
	v_fmac_f32_e32 v75, v50, v50
	v_add_f32_e32 v74, v74, v75
	v_add_f32_e32 v65, v65, v74
	s_waitcnt vmcnt(4)
	v_mul_f32_e32 v74, v45, v45
	v_mul_f32_e32 v75, v47, v47
	v_fmac_f32_e32 v74, v44, v44
	v_fmac_f32_e32 v75, v46, v46
	v_add_f32_e32 v74, v74, v75
	v_add_f32_e32 v65, v65, v74
	s_nop 1
	v_cvt_pk_bf16_f32 v56, v56, v57
	v_cvt_pk_bf16_f32 v57, v58, v59
	s_waitcnt lgkmcnt(0)
	v_add_f32_dpp v65, v65, v65 quad_perm:[1,0,3,2] row_mask:0xf bank_mask:0xf
	s_nop 1
	v_lshl_add_u64 v[74:75], s[84:85], 0, v[66:67]
	v_add_co_u32_e32 v58, vcc, 0x2600000, v74
	s_waitcnt lgkmcnt(0)
	v_add_f32_dpp v65, v65, v65 quad_perm:[2,3,0,1] row_mask:0xf bank_mask:0xf
	s_nop 1
	v_addc_co_u32_e32 v59, vcc, 0, v75, vcc
	global_store_dwordx2 v[58:59], v[56:57], off
	v_cvt_pk_bf16_f32 v40, v40, v41
	s_waitcnt lgkmcnt(0)
	v_add_f32_dpp v65, v65, v65 row_half_mirror row_mask:0xf bank_mask:0xf
	s_nop 1
	v_cvt_pk_bf16_f32 v41, v42, v43
	global_store_dwordx2 v[58:59], v[40:41], off offset:512
	v_cvt_pk_bf16_f32 v40, v36, v37
	v_cvt_pk_bf16_f32 v41, v38, v39
	s_waitcnt lgkmcnt(0)
	v_add_f32_dpp v56, v65, v65 row_mirror row_mask:0xf bank_mask:0xf
	v_mov_b32_e32 v57, v56
	s_nop 1
	v_permlane16_swap_b32_e32 v57, v56
	global_store_dwordx2 v[58:59], v[40:41], off offset:1024
	v_cvt_pk_bf16_f32 v32, v32, v33
	v_cvt_pk_bf16_f32 v33, v34, v35
	global_store_dwordx2 v[58:59], v[32:33], off offset:1536
	s_waitcnt lgkmcnt(0)
	v_add_f32_e32 v36, v57, v56
	v_mov_b32_e32 v37, v36
	s_nop 1
	v_permlane32_swap_b32_e32 v37, v36
	s_and_saveexec_b64 s[20:21], s[2:3]
	s_cbranch_execz .LBB0_97
	s_waitcnt lgkmcnt(0)
	v_add_f32_e32 v32, v37, v36
	global_store_dword v[72:73], v32, off offset:4
.LBB0_97:
	s_or_b64 exec, exec, s[20:21]
	s_waitcnt vmcnt(7)
	v_mul_f32_e32 v32, v29, v29
	v_mul_f32_e32 v33, v31, v31
	v_fmac_f32_e32 v32, v28, v28
	v_fmac_f32_e32 v33, v30, v30
	v_add_f32_e32 v32, v32, v33
	s_waitcnt vmcnt(6)
	v_mul_f32_e32 v33, v25, v25
	v_mul_f32_e32 v34, v27, v27
	v_fmac_f32_e32 v33, v24, v24
	v_fmac_f32_e32 v34, v26, v26
	v_add_f32_e32 v33, v33, v34
	v_add_f32_e32 v32, v32, v33
	s_waitcnt vmcnt(5)
	v_mul_f32_e32 v33, v21, v21
	v_mul_f32_e32 v34, v23, v23
	v_fmac_f32_e32 v33, v20, v20
	v_fmac_f32_e32 v34, v22, v22
	v_add_f32_e32 v33, v33, v34
	v_add_f32_e32 v32, v32, v33
	s_waitcnt vmcnt(4)
	v_mul_f32_e32 v33, v17, v17
	v_mul_f32_e32 v34, v19, v19
	v_fmac_f32_e32 v33, v16, v16
	v_fmac_f32_e32 v34, v18, v18
	v_add_f32_e32 v33, v33, v34
	v_add_f32_e32 v32, v32, v33
	s_nop 1
	v_add_co_u32_e32 v34, vcc, 0x2600000, v74
	s_waitcnt lgkmcnt(0)
	v_add_f32_dpp v32, v32, v32 quad_perm:[1,0,3,2] row_mask:0xf bank_mask:0xf
	s_nop 1
	s_waitcnt lgkmcnt(0)
	v_add_f32_dpp v35, v32, v32 quad_perm:[2,3,0,1] row_mask:0xf bank_mask:0xf
	s_nop 1
	v_cvt_pk_bf16_f32 v32, v60, v61
	v_cvt_pk_bf16_f32 v33, v62, v63
	s_waitcnt lgkmcnt(0)
	v_add_f32_dpp v36, v35, v35 row_half_mirror row_mask:0xf bank_mask:0xf
	s_nop 1
	v_addc_co_u32_e32 v35, vcc, 0, v75, vcc
	global_store_dwordx2 v[34:35], v[32:33], off offset:2048
	v_cvt_pk_bf16_f32 v32, v52, v53
	s_waitcnt lgkmcnt(0)
	v_add_f32_dpp v38, v36, v36 row_mirror row_mask:0xf bank_mask:0xf
	v_mov_b32_e32 v39, v38
	s_nop 1
	v_permlane16_swap_b32_e32 v39, v38
	v_cvt_pk_bf16_f32 v33, v54, v55
	global_store_dwordx2 v[34:35], v[32:33], off offset:2560
	v_cvt_pk_bf16_f32 v36, v48, v49
	v_cvt_pk_bf16_f32 v37, v50, v51
	s_waitcnt lgkmcnt(0)
	v_add_f32_e32 v32, v39, v38
	v_mov_b32_e32 v33, v32
	s_nop 1
	v_permlane32_swap_b32_e32 v33, v32
	global_store_dwordx2 v[34:35], v[36:37], off offset:3072
	v_cvt_pk_bf16_f32 v36, v44, v45
	v_cvt_pk_bf16_f32 v37, v46, v47
	global_store_dwordx2 v[34:35], v[36:37], off offset:3584
	s_and_saveexec_b64 s[20:21], s[2:3]
	s_cbranch_execz .LBB0_99
	s_waitcnt lgkmcnt(0)
	v_add_f32_e32 v32, v33, v32
	global_store_dword v[72:73], v32, off offset:8
.LBB0_99:
	s_or_b64 exec, exec, s[20:21]
	v_mul_f32_e32 v32, v13, v13
	s_waitcnt lgkmcnt(0)
	v_mul_f32_e32 v33, v15, v15
	v_fmac_f32_e32 v32, v12, v12
	v_fmac_f32_e32 v33, v14, v14
	v_add_f32_e32 v32, v32, v33
	v_mul_f32_e32 v33, v9, v9
	v_mul_f32_e32 v34, v11, v11
	v_fmac_f32_e32 v33, v8, v8
	v_fmac_f32_e32 v34, v10, v10
	v_add_f32_e32 v33, v33, v34
	v_add_f32_e32 v32, v32, v33
	v_mul_f32_e32 v33, v5, v5
	v_mul_f32_e32 v34, v7, v7
	v_fmac_f32_e32 v33, v4, v4
	v_fmac_f32_e32 v34, v6, v6
	v_add_f32_e32 v33, v33, v34
	v_add_f32_e32 v32, v32, v33
	v_mul_f32_e32 v33, v1, v1
	v_mul_f32_e32 v34, v3, v3
	v_fmac_f32_e32 v33, v0, v0
	v_fmac_f32_e32 v34, v2, v2
	v_add_f32_e32 v33, v33, v34
	v_add_f32_e32 v32, v32, v33
	s_nop 1
	v_cvt_pk_bf16_f32 v28, v28, v29
	v_cvt_pk_bf16_f32 v29, v30, v31
	v_add_co_u32_e32 v30, vcc, 0x2601000, v74
	s_waitcnt lgkmcnt(0)
	v_add_f32_dpp v32, v32, v32 quad_perm:[1,0,3,2] row_mask:0xf bank_mask:0xf
	s_nop 1
	v_addc_co_u32_e32 v31, vcc, 0, v75, vcc
	global_store_dwordx2 v[30:31], v[28:29], off
	v_cvt_pk_bf16_f32 v24, v24, v25
	s_waitcnt lgkmcnt(0)
	v_add_f32_dpp v32, v32, v32 quad_perm:[2,3,0,1] row_mask:0xf bank_mask:0xf
	s_nop 1
	v_cvt_pk_bf16_f32 v25, v26, v27
	global_store_dwordx2 v[30:31], v[24:25], off offset:512
	v_cvt_pk_bf16_f32 v24, v20, v21
	v_cvt_pk_bf16_f32 v25, v22, v23
	s_waitcnt lgkmcnt(0)
	v_add_f32_dpp v32, v32, v32 row_half_mirror row_mask:0xf bank_mask:0xf
	s_nop 1
	global_store_dwordx2 v[30:31], v[24:25], off offset:1024
	v_cvt_pk_bf16_f32 v16, v16, v17
	v_cvt_pk_bf16_f32 v17, v18, v19
	global_store_dwordx2 v[30:31], v[16:17], off offset:1536
	s_waitcnt lgkmcnt(0)
	v_add_f32_dpp v28, v32, v32 row_mirror row_mask:0xf bank_mask:0xf
	v_mov_b32_e32 v29, v28
	s_nop 1
	v_permlane16_swap_b32_e32 v29, v28
	s_waitcnt lgkmcnt(0)
	v_add_f32_e32 v20, v29, v28
	v_mov_b32_e32 v21, v20
	s_nop 1
	v_permlane32_swap_b32_e32 v21, v20
	s_and_saveexec_b64 s[20:21], s[2:3]
	s_cbranch_execz .LBB0_92
	s_waitcnt lgkmcnt(0)
	v_add_f32_e32 v16, v21, v20
	global_store_dword v[72:73], v16, off offset:12
	s_branch .LBB0_92
